# plus RWKV scan waves s_setprio 2 during segment 2 only
# baseline (speedup 1.0000x reference)
.LBB0_612:
	s_andn2_saveexec_b64 s[0:1], s[0:1]
	s_cbranch_execz .LBB0_624
	s_setprio 2
	v_pk_mul_f32 v[2:3], v[66:67], v[34:35] op_sel_hi:[1,0]
	v_pk_fma_f32 v[2:3], v[70:71], v[32:33], v[2:3] op_sel_hi:[1,0,1]
	v_pk_mul_f32 v[34:35], v[64:65], v[34:35] op_sel:[0,1]
	v_pk_fma_f32 v[2:3], v[62:63], v[28:29], v[2:3] op_sel_hi:[1,0,1]
	v_pk_fma_f32 v[32:33], v[68:69], v[32:33], v[34:35] op_sel:[0,1,0]
	v_pk_fma_f32 v[2:3], v[46:47], v[30:31], v[2:3] op_sel_hi:[1,0,1]
	v_pk_fma_f32 v[28:29], v[60:61], v[28:29], v[32:33] op_sel:[0,1,0]
	v_pk_fma_f32 v[28:29], v[44:45], v[30:31], v[28:29] op_sel:[0,1,0]
	s_and_b32 s20, s25, 1
	v_pk_add_f32 v[2:3], v[2:3], v[28:29]
	s_mul_i32 s21, s20, 0x6000
	s_add_i32 s21, s21, 0
	v_add_f32_dpp v2, v2, v2 quad_perm:[1,0,3,2] row_mask:0xf bank_mask:0xf bound_ctrl:1
	v_add_f32_dpp v3, v3, v3 quad_perm:[1,0,3,2] row_mask:0xf bank_mask:0xf bound_ctrl:1
	s_bitcmp1_b32 s25, 0
	v_lshl_add_u32 v152, v97, 2, s21
	v_mov_b32_dpp v28, v2 quad_perm:[2,3,0,1] row_mask:0xf bank_mask:0xf bound_ctrl:1
	v_mov_b32_dpp v29, v3 quad_perm:[2,3,0,1] row_mask:0xf bank_mask:0xf bound_ctrl:1
	v_lshl_add_u32 v1, v98, 2, s21
	s_cselect_b32 s21, 0x6000, 0
	v_pk_add_f32 v[2:3], v[2:3], v[28:29]
	v_add_u32_e32 v151, s21, v143
	ds_read_b128 v[72:75], v152 offset:5632
	ds_read_b128 v[154:157], v152 offset:5648
	ds_read_b128 v[158:161], v152 offset:9728
	ds_read_b128 v[166:169], v152 offset:9744
	ds_read_b128 v[170:173], v152 offset:13824
	ds_read_b128 v[174:177], v152 offset:13840
	ds_read_b128 v[178:181], v152 offset:17920
	ds_read_b128 v[198:201], v152 offset:17936
	ds_read_b64 v[202:203], v1 offset:22016
	ds_read_b128 v[40:43], v151 offset:1792
	ds_read_b128 v[36:39], v151 offset:1808
	v_add_f32_dpp v28, v2, v2 row_half_mirror row_mask:0xf bank_mask:0xf bound_ctrl:1
	v_add_f32_dpp v29, v3, v3 row_half_mirror row_mask:0xf bank_mask:0xf bound_ctrl:1
	s_lshl_b32 s20, s20, 12
	s_waitcnt lgkmcnt(8)
	v_pk_mul_f32 v[2:3], v[158:159], v[28:29] op_sel_hi:[0,1]
	s_waitcnt lgkmcnt(2)
	v_pk_fma_f32 v[2:3], v[170:171], v[202:203], v[2:3] op_sel_hi:[0,1,1] neg_lo:[0,0,1] neg_hi:[0,0,1]
	v_pk_mul_f32 v[30:31], v[158:159], v[28:29] op_sel:[1,0]
	v_pk_fma_f32 v[2:3], v[70:71], v[72:73], v[2:3] op_sel_hi:[1,0,1]
	v_pk_fma_f32 v[30:31], v[170:171], v[202:203], v[30:31] op_sel:[1,0,0] neg_lo:[0,0,1] neg_hi:[0,0,1]
	v_pk_mul_f32 v[34:35], v[160:161], v[28:29] op_sel_hi:[0,1]
	v_pk_fma_f32 v[32:33], v[68:69], v[72:73], v[30:31] op_sel:[0,1,0]
	v_pk_fma_f32 v[34:35], v[172:173], v[202:203], v[34:35] op_sel_hi:[0,1,1] neg_lo:[0,0,1] neg_hi:[0,0,1]
	v_pk_mul_f32 v[70:71], v[160:161], v[28:29] op_sel:[1,0]
	v_pk_fma_f32 v[34:35], v[66:67], v[74:75], v[34:35] op_sel_hi:[1,0,1]
	v_pk_fma_f32 v[70:71], v[172:173], v[202:203], v[70:71] op_sel:[1,0,0] neg_lo:[0,0,1] neg_hi:[0,0,1]
	v_pk_fma_f32 v[68:69], v[178:179], v[32:33], 0 op_sel:[1,0,0] op_sel_hi:[1,1,0]
	v_pk_fma_f32 v[64:65], v[64:65], v[74:75], v[70:71] op_sel:[0,1,0]
	v_pk_fma_f32 v[66:67], v[180:181], v[64:65], v[68:69] op_sel:[1,0,0]
	v_pk_mul_f32 v[68:69], v[166:167], v[28:29] op_sel_hi:[0,1]
	v_pk_fma_f32 v[68:69], v[174:175], v[202:203], v[68:69] op_sel_hi:[0,1,1] neg_lo:[0,0,1] neg_hi:[0,0,1]
	v_pk_fma_f32 v[62:63], v[62:63], v[154:155], v[68:69] op_sel_hi:[1,0,1]
	v_pk_mul_f32 v[68:69], v[166:167], v[28:29] op_sel:[1,0]
	v_pk_fma_f32 v[30:31], v[178:179], v[2:3], 0 op_sel_hi:[0,1,0]
	v_pk_fma_f32 v[68:69], v[174:175], v[202:203], v[68:69] op_sel:[1,0,0] neg_lo:[0,0,1] neg_hi:[0,0,1]
	v_pk_fma_f32 v[30:31], v[180:181], v[34:35], v[30:31] op_sel_hi:[0,1,1]
	v_pk_fma_f32 v[60:61], v[60:61], v[154:155], v[68:69] op_sel:[0,1,0]
	v_pk_fma_f32 v[70:71], v[198:199], v[60:61], v[66:67] op_sel:[1,0,0]
	v_pk_mul_f32 v[66:67], v[168:169], v[28:29] op_sel_hi:[0,1]
	v_pk_fma_f32 v[66:67], v[176:177], v[202:203], v[66:67] op_sel_hi:[0,1,1] neg_lo:[0,0,1] neg_hi:[0,0,1]
	v_pk_mul_f32 v[28:29], v[168:169], v[28:29] op_sel:[1,0]
	v_pk_fma_f32 v[30:31], v[198:199], v[62:63], v[30:31] op_sel_hi:[0,1,1]
	v_pk_fma_f32 v[66:67], v[46:47], v[156:157], v[66:67] op_sel_hi:[1,0,1]
	v_pk_fma_f32 v[28:29], v[176:177], v[202:203], v[28:29] op_sel:[1,0,0] neg_lo:[0,0,1] neg_hi:[0,0,1]
	v_pk_fma_f32 v[68:69], v[44:45], v[156:157], v[28:29] op_sel:[0,1,0]
	v_pk_fma_f32 v[28:29], v[200:201], v[66:67], v[30:31] op_sel_hi:[0,1,1]
	v_pk_fma_f32 v[30:31], v[200:201], v[68:69], v[70:71] op_sel:[1,0,0]
	v_pk_add_f32 v[28:29], v[28:29], v[30:31]
	v_add_u32_e32 v153, s20, v99
	s_nop 0
	v_add_f32_dpp v28, v28, v28 quad_perm:[1,0,3,2] row_mask:0xf bank_mask:0xf bound_ctrl:1
	v_add_f32_dpp v29, v29, v29 quad_perm:[1,0,3,2] row_mask:0xf bank_mask:0xf bound_ctrl:1
	s_nop 0
	v_add_f32_dpp v28, v28, v28 quad_perm:[2,3,0,1] row_mask:0xf bank_mask:0xf bound_ctrl:1
	v_add_f32_dpp v29, v29, v29 quad_perm:[2,3,0,1] row_mask:0xf bank_mask:0xf bound_ctrl:1
	s_nop 0
	v_mov_b32_dpp v30, v28 row_half_mirror row_mask:0xf bank_mask:0xf bound_ctrl:1
	v_mov_b32_dpp v31, v29 row_half_mirror row_mask:0xf bank_mask:0xf bound_ctrl:1
	s_and_saveexec_b64 s[20:21], s[14:15]
	v_pk_add_f32 v[28:29], v[28:29], v[30:31]
	ds_write_b64 v153, v[28:29] offset:50688
	s_or_b64 exec, exec, s[20:21]
	s_waitcnt lgkmcnt(1)
	v_pk_mul_f32 v[202:203], v[42:43], v[34:35] op_sel_hi:[0,1]
	v_pk_fma_f32 v[202:203], v[40:41], v[2:3], v[202:203] op_sel_hi:[0,1,1]
	v_pk_mul_f32 v[42:43], v[42:43], v[64:65] op_sel:[1,0]
	v_pk_fma_f32 v[40:41], v[40:41], v[32:33], v[42:43] op_sel:[1,0,0]
	s_waitcnt lgkmcnt(0)
	v_pk_fma_f32 v[42:43], v[36:37], v[62:63], v[202:203] op_sel_hi:[0,1,1]
	v_pk_fma_f32 v[36:37], v[36:37], v[60:61], v[40:41] op_sel:[1,0,0]
	v_pk_fma_f32 v[40:41], v[38:39], v[66:67], v[42:43] op_sel_hi:[0,1,1]
	v_pk_fma_f32 v[36:37], v[38:39], v[68:69], v[36:37] op_sel:[1,0,0]
	v_pk_add_f32 v[36:37], v[40:41], v[36:37]
	ds_read_b128 v[70:73], v152 offset:5888
	ds_read_b128 v[154:157], v152 offset:5904
	ds_read_b128 v[158:161], v152 offset:9984
	ds_read_b128 v[166:169], v152 offset:10000
	ds_read_b128 v[170:173], v152 offset:14080
	ds_read_b128 v[174:177], v152 offset:14096
	ds_read_b128 v[178:181], v152 offset:18176
	ds_read_b128 v[198:201], v152 offset:18192
	ds_read_b64 v[74:75], v1 offset:22272
	ds_read_b128 v[44:47], v151 offset:2048
	ds_read_b128 v[28:31], v151 offset:2064
	v_add_f32_dpp v36, v36, v36 quad_perm:[1,0,3,2] row_mask:0xf bank_mask:0xf bound_ctrl:1
	v_add_f32_dpp v37, v37, v37 quad_perm:[1,0,3,2] row_mask:0xf bank_mask:0xf bound_ctrl:1
	s_nop 0
	v_add_f32_dpp v36, v36, v36 quad_perm:[2,3,0,1] row_mask:0xf bank_mask:0xf bound_ctrl:1
	v_add_f32_dpp v37, v37, v37 quad_perm:[2,3,0,1] row_mask:0xf bank_mask:0xf bound_ctrl:1
	s_nop 0
	v_add_f32_dpp v40, v36, v36 row_half_mirror row_mask:0xf bank_mask:0xf bound_ctrl:1
	v_add_f32_dpp v41, v37, v37 row_half_mirror row_mask:0xf bank_mask:0xf bound_ctrl:1
	s_waitcnt lgkmcnt(8)
	v_pk_mul_f32 v[36:37], v[158:159], v[40:41] op_sel_hi:[0,1]
	s_waitcnt lgkmcnt(2)
	v_pk_fma_f32 v[36:37], v[170:171], v[74:75], v[36:37] op_sel_hi:[0,1,1] neg_lo:[0,0,1] neg_hi:[0,0,1]
	v_pk_fma_f32 v[2:3], v[2:3], v[70:71], v[36:37] op_sel_hi:[1,0,1]
	v_pk_mul_f32 v[36:37], v[158:159], v[40:41] op_sel:[1,0]
	v_pk_mul_f32 v[38:39], v[160:161], v[40:41] op_sel_hi:[0,1]
	v_pk_fma_f32 v[36:37], v[170:171], v[74:75], v[36:37] op_sel:[1,0,0] neg_lo:[0,0,1] neg_hi:[0,0,1]
	v_pk_fma_f32 v[38:39], v[172:173], v[74:75], v[38:39] op_sel_hi:[0,1,1] neg_lo:[0,0,1] neg_hi:[0,0,1]
	v_pk_fma_f32 v[36:37], v[32:33], v[70:71], v[36:37] op_sel:[0,1,0]
	v_pk_fma_f32 v[38:39], v[34:35], v[72:73], v[38:39] op_sel_hi:[1,0,1]
	v_pk_mul_f32 v[70:71], v[160:161], v[40:41] op_sel:[1,0]
	v_pk_fma_f32 v[70:71], v[172:173], v[74:75], v[70:71] op_sel:[1,0,0] neg_lo:[0,0,1] neg_hi:[0,0,1]
	v_pk_fma_f32 v[42:43], v[178:179], v[36:37], 0 op_sel:[1,0,0] op_sel_hi:[1,1,0]
	v_pk_fma_f32 v[64:65], v[64:65], v[72:73], v[70:71] op_sel:[0,1,0]
	v_pk_fma_f32 v[34:35], v[180:181], v[64:65], v[42:43] op_sel:[1,0,0]
	v_pk_mul_f32 v[42:43], v[166:167], v[40:41] op_sel_hi:[0,1]
	v_pk_fma_f32 v[42:43], v[174:175], v[74:75], v[42:43] op_sel_hi:[0,1,1] neg_lo:[0,0,1] neg_hi:[0,0,1]
	v_pk_fma_f32 v[62:63], v[62:63], v[154:155], v[42:43] op_sel_hi:[1,0,1]
	v_pk_mul_f32 v[42:43], v[166:167], v[40:41] op_sel:[1,0]
	v_pk_fma_f32 v[42:43], v[174:175], v[74:75], v[42:43] op_sel:[1,0,0] neg_lo:[0,0,1] neg_hi:[0,0,1]
	v_pk_fma_f32 v[32:33], v[178:179], v[2:3], 0 op_sel_hi:[0,1,0]
	v_pk_fma_f32 v[60:61], v[60:61], v[154:155], v[42:43] op_sel:[0,1,0]
	v_pk_mul_f32 v[42:43], v[168:169], v[40:41] op_sel_hi:[0,1]
	v_pk_fma_f32 v[42:43], v[176:177], v[74:75], v[42:43] op_sel_hi:[0,1,1] neg_lo:[0,0,1] neg_hi:[0,0,1]
	v_pk_mul_f32 v[40:41], v[168:169], v[40:41] op_sel:[1,0]
	v_pk_fma_f32 v[32:33], v[180:181], v[38:39], v[32:33] op_sel_hi:[0,1,1]
	v_pk_fma_f32 v[66:67], v[66:67], v[156:157], v[42:43] op_sel_hi:[1,0,1]
	v_pk_fma_f32 v[40:41], v[176:177], v[74:75], v[40:41] op_sel:[1,0,0] neg_lo:[0,0,1] neg_hi:[0,0,1]
	v_pk_fma_f32 v[32:33], v[198:199], v[62:63], v[32:33] op_sel_hi:[0,1,1]
	v_pk_fma_f32 v[34:35], v[198:199], v[60:61], v[34:35] op_sel:[1,0,0]
	v_pk_fma_f32 v[68:69], v[68:69], v[156:157], v[40:41] op_sel:[0,1,0]
	v_pk_fma_f32 v[32:33], v[200:201], v[66:67], v[32:33] op_sel_hi:[0,1,1]
	v_pk_fma_f32 v[34:35], v[200:201], v[68:69], v[34:35] op_sel:[1,0,0]
	v_pk_add_f32 v[32:33], v[32:33], v[34:35]
	s_nop 1
	v_add_f32_dpp v32, v32, v32 quad_perm:[1,0,3,2] row_mask:0xf bank_mask:0xf bound_ctrl:1
	v_add_f32_dpp v33, v33, v33 quad_perm:[1,0,3,2] row_mask:0xf bank_mask:0xf bound_ctrl:1
	s_nop 0
	v_add_f32_dpp v32, v32, v32 quad_perm:[2,3,0,1] row_mask:0xf bank_mask:0xf bound_ctrl:1
	v_add_f32_dpp v33, v33, v33 quad_perm:[2,3,0,1] row_mask:0xf bank_mask:0xf bound_ctrl:1
	s_nop 0
	v_mov_b32_dpp v34, v32 row_half_mirror row_mask:0xf bank_mask:0xf bound_ctrl:1
	v_mov_b32_dpp v35, v33 row_half_mirror row_mask:0xf bank_mask:0xf bound_ctrl:1
	s_and_saveexec_b64 s[20:21], s[14:15]
	v_pk_add_f32 v[32:33], v[32:33], v[34:35]
	ds_write_b64 v153, v[32:33] offset:50944
	s_or_b64 exec, exec, s[20:21]
	s_waitcnt lgkmcnt(1)
	v_pk_mul_f32 v[202:203], v[46:47], v[38:39] op_sel_hi:[0,1]
	v_pk_fma_f32 v[202:203], v[44:45], v[2:3], v[202:203] op_sel_hi:[0,1,1]
	v_pk_mul_f32 v[46:47], v[46:47], v[64:65] op_sel:[1,0]
	v_pk_fma_f32 v[44:45], v[44:45], v[36:37], v[46:47] op_sel:[1,0,0]
	s_waitcnt lgkmcnt(0)
	v_pk_fma_f32 v[46:47], v[28:29], v[62:63], v[202:203] op_sel_hi:[0,1,1]
	v_pk_fma_f32 v[28:29], v[28:29], v[60:61], v[44:45] op_sel:[1,0,0]
	v_pk_fma_f32 v[44:45], v[30:31], v[66:67], v[46:47] op_sel_hi:[0,1,1]
	v_pk_fma_f32 v[28:29], v[30:31], v[68:69], v[28:29] op_sel:[1,0,0]
	v_pk_add_f32 v[28:29], v[44:45], v[28:29]
	ds_read_b128 v[70:73], v152 offset:6144
	ds_read_b128 v[154:157], v152 offset:6160
	ds_read_b128 v[158:161], v152 offset:10240
	ds_read_b128 v[166:169], v152 offset:10256
	ds_read_b128 v[170:173], v152 offset:14336
	ds_read_b128 v[174:177], v152 offset:14352
	ds_read_b128 v[178:181], v152 offset:18432
	ds_read_b128 v[198:201], v152 offset:18448
	ds_read_b64 v[74:75], v1 offset:22528
	ds_read_b128 v[40:43], v151 offset:2304
	ds_read_b128 v[32:35], v151 offset:2320
	v_add_f32_dpp v28, v28, v28 quad_perm:[1,0,3,2] row_mask:0xf bank_mask:0xf bound_ctrl:1
	v_add_f32_dpp v29, v29, v29 quad_perm:[1,0,3,2] row_mask:0xf bank_mask:0xf bound_ctrl:1
	s_nop 0
	v_add_f32_dpp v28, v28, v28 quad_perm:[2,3,0,1] row_mask:0xf bank_mask:0xf bound_ctrl:1
	v_add_f32_dpp v29, v29, v29 quad_perm:[2,3,0,1] row_mask:0xf bank_mask:0xf bound_ctrl:1
	s_nop 0
	v_add_f32_dpp v44, v28, v28 row_half_mirror row_mask:0xf bank_mask:0xf bound_ctrl:1
	v_add_f32_dpp v45, v29, v29 row_half_mirror row_mask:0xf bank_mask:0xf bound_ctrl:1
	s_waitcnt lgkmcnt(8)
	v_pk_mul_f32 v[28:29], v[158:159], v[44:45] op_sel_hi:[0,1]
	s_waitcnt lgkmcnt(2)
	v_pk_fma_f32 v[28:29], v[170:171], v[74:75], v[28:29] op_sel_hi:[0,1,1] neg_lo:[0,0,1] neg_hi:[0,0,1]
	v_pk_fma_f32 v[2:3], v[2:3], v[70:71], v[28:29] op_sel_hi:[1,0,1]
	v_pk_mul_f32 v[28:29], v[158:159], v[44:45] op_sel:[1,0]
	v_pk_mul_f32 v[30:31], v[160:161], v[44:45] op_sel_hi:[0,1]
	v_pk_fma_f32 v[28:29], v[170:171], v[74:75], v[28:29] op_sel:[1,0,0] neg_lo:[0,0,1] neg_hi:[0,0,1]
	v_pk_fma_f32 v[30:31], v[172:173], v[74:75], v[30:31] op_sel_hi:[0,1,1] neg_lo:[0,0,1] neg_hi:[0,0,1]
	v_pk_fma_f32 v[28:29], v[36:37], v[70:71], v[28:29] op_sel:[0,1,0]
	v_pk_fma_f32 v[30:31], v[38:39], v[72:73], v[30:31] op_sel_hi:[1,0,1]
	v_pk_mul_f32 v[70:71], v[160:161], v[44:45] op_sel:[1,0]
	v_pk_fma_f32 v[70:71], v[172:173], v[74:75], v[70:71] op_sel:[1,0,0] neg_lo:[0,0,1] neg_hi:[0,0,1]
	v_pk_fma_f32 v[46:47], v[178:179], v[28:29], 0 op_sel:[1,0,0] op_sel_hi:[1,1,0]
	v_pk_fma_f32 v[64:65], v[64:65], v[72:73], v[70:71] op_sel:[0,1,0]
	v_pk_fma_f32 v[38:39], v[180:181], v[64:65], v[46:47] op_sel:[1,0,0]
	v_pk_mul_f32 v[46:47], v[166:167], v[44:45] op_sel_hi:[0,1]
	v_pk_fma_f32 v[46:47], v[174:175], v[74:75], v[46:47] op_sel_hi:[0,1,1] neg_lo:[0,0,1] neg_hi:[0,0,1]
	v_pk_fma_f32 v[62:63], v[62:63], v[154:155], v[46:47] op_sel_hi:[1,0,1]
	v_pk_mul_f32 v[46:47], v[166:167], v[44:45] op_sel:[1,0]
	v_pk_fma_f32 v[46:47], v[174:175], v[74:75], v[46:47] op_sel:[1,0,0] neg_lo:[0,0,1] neg_hi:[0,0,1]
	v_pk_fma_f32 v[36:37], v[178:179], v[2:3], 0 op_sel_hi:[0,1,0]
	v_pk_fma_f32 v[60:61], v[60:61], v[154:155], v[46:47] op_sel:[0,1,0]
	v_pk_mul_f32 v[46:47], v[168:169], v[44:45] op_sel_hi:[0,1]
	v_pk_fma_f32 v[46:47], v[176:177], v[74:75], v[46:47] op_sel_hi:[0,1,1] neg_lo:[0,0,1] neg_hi:[0,0,1]
	v_pk_mul_f32 v[44:45], v[168:169], v[44:45] op_sel:[1,0]
	v_pk_fma_f32 v[36:37], v[180:181], v[30:31], v[36:37] op_sel_hi:[0,1,1]
	v_pk_fma_f32 v[66:67], v[66:67], v[156:157], v[46:47] op_sel_hi:[1,0,1]
	v_pk_fma_f32 v[44:45], v[176:177], v[74:75], v[44:45] op_sel:[1,0,0] neg_lo:[0,0,1] neg_hi:[0,0,1]
	v_pk_fma_f32 v[36:37], v[198:199], v[62:63], v[36:37] op_sel_hi:[0,1,1]
	v_pk_fma_f32 v[38:39], v[198:199], v[60:61], v[38:39] op_sel:[1,0,0]
	v_pk_fma_f32 v[68:69], v[68:69], v[156:157], v[44:45] op_sel:[0,1,0]
	v_pk_fma_f32 v[36:37], v[200:201], v[66:67], v[36:37] op_sel_hi:[0,1,1]
	v_pk_fma_f32 v[38:39], v[200:201], v[68:69], v[38:39] op_sel:[1,0,0]
	v_pk_add_f32 v[36:37], v[36:37], v[38:39]
	s_nop 1
	v_add_f32_dpp v36, v36, v36 quad_perm:[1,0,3,2] row_mask:0xf bank_mask:0xf bound_ctrl:1
	v_add_f32_dpp v37, v37, v37 quad_perm:[1,0,3,2] row_mask:0xf bank_mask:0xf bound_ctrl:1
	s_nop 0
	v_add_f32_dpp v36, v36, v36 quad_perm:[2,3,0,1] row_mask:0xf bank_mask:0xf bound_ctrl:1
	v_add_f32_dpp v37, v37, v37 quad_perm:[2,3,0,1] row_mask:0xf bank_mask:0xf bound_ctrl:1
	s_nop 0
	v_mov_b32_dpp v38, v36 row_half_mirror row_mask:0xf bank_mask:0xf bound_ctrl:1
	v_mov_b32_dpp v39, v37 row_half_mirror row_mask:0xf bank_mask:0xf bound_ctrl:1
	s_and_saveexec_b64 s[20:21], s[14:15]
	v_pk_add_f32 v[36:37], v[36:37], v[38:39]
	ds_write_b64 v153, v[36:37] offset:51200
	s_or_b64 exec, exec, s[20:21]
	s_waitcnt lgkmcnt(1)
	v_pk_mul_f32 v[202:203], v[42:43], v[30:31] op_sel_hi:[0,1]
	v_pk_fma_f32 v[202:203], v[40:41], v[2:3], v[202:203] op_sel_hi:[0,1,1]
	v_pk_mul_f32 v[42:43], v[42:43], v[64:65] op_sel:[1,0]
	v_pk_fma_f32 v[40:41], v[40:41], v[28:29], v[42:43] op_sel:[1,0,0]
	s_waitcnt lgkmcnt(0)
	v_pk_fma_f32 v[42:43], v[32:33], v[62:63], v[202:203] op_sel_hi:[0,1,1]
	v_pk_fma_f32 v[32:33], v[32:33], v[60:61], v[40:41] op_sel:[1,0,0]
	v_pk_fma_f32 v[40:41], v[34:35], v[66:67], v[42:43] op_sel_hi:[0,1,1]
	v_pk_fma_f32 v[32:33], v[34:35], v[68:69], v[32:33] op_sel:[1,0,0]
	v_pk_add_f32 v[32:33], v[40:41], v[32:33]
	ds_read_b128 v[70:73], v152 offset:6400
	ds_read_b128 v[154:157], v152 offset:6416
	ds_read_b128 v[158:161], v152 offset:10496
	ds_read_b128 v[166:169], v152 offset:10512
	ds_read_b128 v[170:173], v152 offset:14592
	ds_read_b128 v[174:177], v152 offset:14608
	ds_read_b128 v[178:181], v152 offset:18688
	ds_read_b128 v[198:201], v152 offset:18704
	ds_read_b64 v[74:75], v1 offset:22784
	ds_read_b128 v[44:47], v151 offset:2560
	ds_read_b128 v[36:39], v151 offset:2576
	v_add_f32_dpp v32, v32, v32 quad_perm:[1,0,3,2] row_mask:0xf bank_mask:0xf bound_ctrl:1
	v_add_f32_dpp v33, v33, v33 quad_perm:[1,0,3,2] row_mask:0xf bank_mask:0xf bound_ctrl:1
	s_nop 0
	v_add_f32_dpp v32, v32, v32 quad_perm:[2,3,0,1] row_mask:0xf bank_mask:0xf bound_ctrl:1
	v_add_f32_dpp v33, v33, v33 quad_perm:[2,3,0,1] row_mask:0xf bank_mask:0xf bound_ctrl:1
	s_nop 0
	v_add_f32_dpp v32, v32, v32 row_half_mirror row_mask:0xf bank_mask:0xf bound_ctrl:1
	v_add_f32_dpp v33, v33, v33 row_half_mirror row_mask:0xf bank_mask:0xf bound_ctrl:1
	s_waitcnt lgkmcnt(8)
	v_pk_mul_f32 v[34:35], v[158:159], v[32:33] op_sel_hi:[0,1]
	s_waitcnt lgkmcnt(2)
	v_pk_fma_f32 v[34:35], v[170:171], v[74:75], v[34:35] op_sel_hi:[0,1,1] neg_lo:[0,0,1] neg_hi:[0,0,1]
	v_pk_fma_f32 v[2:3], v[2:3], v[70:71], v[34:35] op_sel_hi:[1,0,1]
	v_pk_mul_f32 v[34:35], v[158:159], v[32:33] op_sel:[1,0]
	v_pk_mul_f32 v[42:43], v[160:161], v[32:33] op_sel_hi:[0,1]
	v_pk_fma_f32 v[34:35], v[170:171], v[74:75], v[34:35] op_sel:[1,0,0] neg_lo:[0,0,1] neg_hi:[0,0,1]
	v_pk_fma_f32 v[42:43], v[172:173], v[74:75], v[42:43] op_sel_hi:[0,1,1] neg_lo:[0,0,1] neg_hi:[0,0,1]
	v_pk_fma_f32 v[40:41], v[28:29], v[70:71], v[34:35] op_sel:[0,1,0]
	v_pk_fma_f32 v[42:43], v[30:31], v[72:73], v[42:43] op_sel_hi:[1,0,1]
	v_pk_mul_f32 v[70:71], v[160:161], v[32:33] op_sel:[1,0]
	v_pk_fma_f32 v[70:71], v[172:173], v[74:75], v[70:71] op_sel:[1,0,0] neg_lo:[0,0,1] neg_hi:[0,0,1]
	v_pk_fma_f32 v[34:35], v[178:179], v[40:41], 0 op_sel:[1,0,0] op_sel_hi:[1,1,0]
	v_pk_fma_f32 v[64:65], v[64:65], v[72:73], v[70:71] op_sel:[0,1,0]
	v_pk_fma_f32 v[30:31], v[180:181], v[64:65], v[34:35] op_sel:[1,0,0]
	v_pk_mul_f32 v[34:35], v[166:167], v[32:33] op_sel_hi:[0,1]
	v_pk_fma_f32 v[34:35], v[174:175], v[74:75], v[34:35] op_sel_hi:[0,1,1] neg_lo:[0,0,1] neg_hi:[0,0,1]
	v_pk_fma_f32 v[62:63], v[62:63], v[154:155], v[34:35] op_sel_hi:[1,0,1]
	v_pk_mul_f32 v[34:35], v[166:167], v[32:33] op_sel:[1,0]
	v_pk_fma_f32 v[28:29], v[178:179], v[2:3], 0 op_sel_hi:[0,1,0]
	v_pk_fma_f32 v[34:35], v[174:175], v[74:75], v[34:35] op_sel:[1,0,0] neg_lo:[0,0,1] neg_hi:[0,0,1]
	v_pk_fma_f32 v[60:61], v[60:61], v[154:155], v[34:35] op_sel:[0,1,0]
	v_pk_mul_f32 v[34:35], v[168:169], v[32:33] op_sel_hi:[0,1]
	v_pk_fma_f32 v[34:35], v[176:177], v[74:75], v[34:35] op_sel_hi:[0,1,1] neg_lo:[0,0,1] neg_hi:[0,0,1]
	v_pk_fma_f32 v[72:73], v[66:67], v[156:157], v[34:35] op_sel_hi:[1,0,1]
	v_pk_mul_f32 v[32:33], v[168:169], v[32:33] op_sel:[1,0]
	v_pk_fma_f32 v[28:29], v[180:181], v[42:43], v[28:29] op_sel_hi:[0,1,1]
	v_pk_fma_f32 v[32:33], v[176:177], v[74:75], v[32:33] op_sel:[1,0,0] neg_lo:[0,0,1] neg_hi:[0,0,1]
	v_pk_fma_f32 v[28:29], v[198:199], v[62:63], v[28:29] op_sel_hi:[0,1,1]
	v_pk_fma_f32 v[30:31], v[198:199], v[60:61], v[30:31] op_sel:[1,0,0]
	v_pk_fma_f32 v[74:75], v[68:69], v[156:157], v[32:33] op_sel:[0,1,0]
	v_pk_fma_f32 v[28:29], v[200:201], v[72:73], v[28:29] op_sel_hi:[0,1,1]
	v_pk_fma_f32 v[30:31], v[200:201], v[74:75], v[30:31] op_sel:[1,0,0]
	v_pk_add_f32 v[28:29], v[28:29], v[30:31]
	s_nop 1
	v_add_f32_dpp v28, v28, v28 quad_perm:[1,0,3,2] row_mask:0xf bank_mask:0xf bound_ctrl:1
	v_add_f32_dpp v29, v29, v29 quad_perm:[1,0,3,2] row_mask:0xf bank_mask:0xf bound_ctrl:1
	s_nop 0
	v_add_f32_dpp v28, v28, v28 quad_perm:[2,3,0,1] row_mask:0xf bank_mask:0xf bound_ctrl:1
	v_add_f32_dpp v29, v29, v29 quad_perm:[2,3,0,1] row_mask:0xf bank_mask:0xf bound_ctrl:1
	s_nop 0
	v_mov_b32_dpp v30, v28 row_half_mirror row_mask:0xf bank_mask:0xf bound_ctrl:1
	v_mov_b32_dpp v31, v29 row_half_mirror row_mask:0xf bank_mask:0xf bound_ctrl:1
	s_and_saveexec_b64 s[20:21], s[14:15]
	v_pk_add_f32 v[28:29], v[28:29], v[30:31]
	ds_write_b64 v153, v[28:29] offset:51456
	s_or_b64 exec, exec, s[20:21]
	s_waitcnt lgkmcnt(1)
	v_pk_mul_f32 v[66:67], v[46:47], v[42:43] op_sel_hi:[0,1]
	v_pk_fma_f32 v[66:67], v[44:45], v[2:3], v[66:67] op_sel_hi:[0,1,1]
	v_pk_mul_f32 v[46:47], v[46:47], v[64:65] op_sel:[1,0]
	v_pk_fma_f32 v[44:45], v[44:45], v[40:41], v[46:47] op_sel:[1,0,0]
	s_waitcnt lgkmcnt(0)
	v_pk_fma_f32 v[46:47], v[36:37], v[62:63], v[66:67] op_sel_hi:[0,1,1]
	v_pk_fma_f32 v[36:37], v[36:37], v[60:61], v[44:45] op_sel:[1,0,0]
	v_pk_fma_f32 v[44:45], v[38:39], v[72:73], v[46:47] op_sel_hi:[0,1,1]
	v_pk_fma_f32 v[36:37], v[38:39], v[74:75], v[36:37] op_sel:[1,0,0]
	v_pk_add_f32 v[36:37], v[44:45], v[36:37]
	ds_read_b128 v[154:157], v152 offset:6656
	ds_read_b128 v[158:161], v152 offset:6672
	ds_read_b128 v[166:169], v152 offset:10752
	ds_read_b128 v[170:173], v152 offset:10768
	ds_read_b128 v[174:177], v152 offset:14848
	ds_read_b128 v[178:181], v152 offset:14864
	ds_read_b128 v[198:201], v152 offset:18944
	ds_read_b128 v[202:205], v152 offset:18960
	ds_read_b64 v[206:207], v1 offset:23040
	ds_read_b128 v[32:35], v151 offset:2816
	ds_read_b128 v[28:31], v151 offset:2832
	v_add_f32_dpp v36, v36, v36 quad_perm:[1,0,3,2] row_mask:0xf bank_mask:0xf bound_ctrl:1
	v_add_f32_dpp v37, v37, v37 quad_perm:[1,0,3,2] row_mask:0xf bank_mask:0xf bound_ctrl:1
	s_nop 0
	s_waitcnt lgkmcnt(6)
	v_add_f32_dpp v36, v36, v36 quad_perm:[2,3,0,1] row_mask:0xf bank_mask:0xf bound_ctrl:1
	v_add_f32_dpp v37, v37, v37 quad_perm:[2,3,0,1] row_mask:0xf bank_mask:0xf bound_ctrl:1
	s_nop 0
	v_add_f32_dpp v36, v36, v36 row_half_mirror row_mask:0xf bank_mask:0xf bound_ctrl:1
	v_add_f32_dpp v37, v37, v37 row_half_mirror row_mask:0xf bank_mask:0xf bound_ctrl:1
	s_nop 0
	v_pk_mul_f32 v[38:39], v[166:167], v[36:37] op_sel_hi:[0,1]
	s_waitcnt lgkmcnt(2)
	v_pk_fma_f32 v[38:39], v[174:175], v[206:207], v[38:39] op_sel_hi:[0,1,1] neg_lo:[0,0,1] neg_hi:[0,0,1]
	v_pk_fma_f32 v[70:71], v[2:3], v[154:155], v[38:39] op_sel_hi:[1,0,1]
	v_pk_mul_f32 v[2:3], v[166:167], v[36:37] op_sel:[1,0]
	s_nop 0
	v_pk_fma_f32 v[2:3], v[174:175], v[206:207], v[2:3] op_sel:[1,0,0] neg_lo:[0,0,1] neg_hi:[0,0,1]
	s_nop 0
	v_pk_fma_f32 v[68:69], v[40:41], v[154:155], v[2:3] op_sel:[0,1,0]
	v_pk_mul_f32 v[40:41], v[168:169], v[36:37] op_sel_hi:[0,1]
	v_pk_fma_f32 v[40:41], v[176:177], v[206:207], v[40:41] op_sel_hi:[0,1,1] neg_lo:[0,0,1] neg_hi:[0,0,1]
	v_pk_fma_f32 v[66:67], v[42:43], v[156:157], v[40:41] op_sel_hi:[1,0,1]
	v_pk_mul_f32 v[42:43], v[168:169], v[36:37] op_sel:[1,0]
	v_pk_fma_f32 v[42:43], v[176:177], v[206:207], v[42:43] op_sel:[1,0,0] neg_lo:[0,0,1] neg_hi:[0,0,1]
	v_pk_fma_f32 v[38:39], v[198:199], v[68:69], 0 op_sel:[1,0,0] op_sel_hi:[1,1,0]
	v_pk_fma_f32 v[64:65], v[64:65], v[156:157], v[42:43] op_sel:[0,1,0]
	v_pk_fma_f32 v[38:39], v[200:201], v[64:65], v[38:39] op_sel:[1,0,0]
	v_pk_mul_f32 v[40:41], v[170:171], v[36:37] op_sel_hi:[0,1]
	v_pk_fma_f32 v[40:41], v[178:179], v[206:207], v[40:41] op_sel_hi:[0,1,1] neg_lo:[0,0,1] neg_hi:[0,0,1]
	v_pk_fma_f32 v[62:63], v[62:63], v[158:159], v[40:41] op_sel_hi:[1,0,1]
	v_pk_mul_f32 v[40:41], v[170:171], v[36:37] op_sel:[1,0]
	v_mov_b32_e32 v42, v173
	v_pk_fma_f32 v[40:41], v[178:179], v[206:207], v[40:41] op_sel:[1,0,0] neg_lo:[0,0,1] neg_hi:[0,0,1]
	v_pk_fma_f32 v[2:3], v[198:199], v[70:71], 0 op_sel_hi:[0,1,0]
	v_pk_fma_f32 v[60:61], v[60:61], v[158:159], v[40:41] op_sel:[0,1,0]
	v_pk_mul_f32 v[40:41], v[172:173], v[36:37] op_sel_hi:[0,1]
	v_pk_fma_f32 v[40:41], v[180:181], v[206:207], v[40:41] op_sel_hi:[0,1,1] neg_lo:[0,0,1] neg_hi:[0,0,1]
	v_pk_mul_f32 v[36:37], v[42:43], v[36:37] op_sel_hi:[0,1]
	v_pk_fma_f32 v[2:3], v[200:201], v[66:67], v[2:3] op_sel_hi:[0,1,1]
	v_pk_fma_f32 v[46:47], v[72:73], v[160:161], v[40:41] op_sel_hi:[1,0,1]
	v_mov_b32_e32 v40, v161
	v_pk_fma_f32 v[36:37], v[180:181], v[206:207], v[36:37] op_sel:[1,0,0] neg_lo:[0,0,1] neg_hi:[0,0,1]
	v_pk_fma_f32 v[2:3], v[202:203], v[62:63], v[2:3] op_sel_hi:[0,1,1]
	v_pk_fma_f32 v[38:39], v[202:203], v[60:61], v[38:39] op_sel:[1,0,0]
	v_pk_fma_f32 v[44:45], v[74:75], v[40:41], v[36:37] op_sel_hi:[1,0,1]
	v_pk_fma_f32 v[2:3], v[204:205], v[46:47], v[2:3] op_sel_hi:[0,1,1]
	v_pk_fma_f32 v[36:37], v[204:205], v[44:45], v[38:39] op_sel:[1,0,0]
	v_pk_add_f32 v[2:3], v[2:3], v[36:37]
	s_nop 1
	v_add_f32_dpp v2, v2, v2 quad_perm:[1,0,3,2] row_mask:0xf bank_mask:0xf bound_ctrl:1
	v_add_f32_dpp v3, v3, v3 quad_perm:[1,0,3,2] row_mask:0xf bank_mask:0xf bound_ctrl:1
	s_nop 0
	v_add_f32_dpp v2, v2, v2 quad_perm:[2,3,0,1] row_mask:0xf bank_mask:0xf bound_ctrl:1
	v_add_f32_dpp v3, v3, v3 quad_perm:[2,3,0,1] row_mask:0xf bank_mask:0xf bound_ctrl:1
	s_nop 0
	v_mov_b32_dpp v36, v2 row_half_mirror row_mask:0xf bank_mask:0xf bound_ctrl:1
	v_mov_b32_dpp v37, v3 row_half_mirror row_mask:0xf bank_mask:0xf bound_ctrl:1
	s_and_saveexec_b64 s[20:21], s[14:15]
	v_pk_add_f32 v[2:3], v[2:3], v[36:37]
	ds_write_b64 v153, v[2:3] offset:51712
	s_or_b64 exec, exec, s[20:21]

.LBB0_635:
	s_andn2_saveexec_b64 s[0:1], s[0:1]
	s_cbranch_execz .LBB0_576
	s_setprio 0
	v_pk_mul_f32 v[2:3], v[66:67], v[34:35] op_sel_hi:[1,0]
	v_pk_fma_f32 v[2:3], v[70:71], v[32:33], v[2:3] op_sel_hi:[1,0,1]
	v_pk_mul_f32 v[34:35], v[64:65], v[34:35] op_sel:[0,1]
	v_pk_fma_f32 v[2:3], v[62:63], v[28:29], v[2:3] op_sel_hi:[1,0,1]
	v_pk_fma_f32 v[32:33], v[68:69], v[32:33], v[34:35] op_sel:[0,1,0]
	v_pk_fma_f32 v[2:3], v[46:47], v[30:31], v[2:3] op_sel_hi:[1,0,1]
	v_pk_fma_f32 v[28:29], v[60:61], v[28:29], v[32:33] op_sel:[0,1,0]
	v_pk_fma_f32 v[28:29], v[44:45], v[30:31], v[28:29] op_sel:[0,1,0]
	s_and_b32 s20, s25, 1
	v_pk_add_f32 v[2:3], v[2:3], v[28:29]
	s_mul_i32 s21, s20, 0x6000
	s_add_i32 s21, s21, 0
	v_add_f32_dpp v2, v2, v2 quad_perm:[1,0,3,2] row_mask:0xf bank_mask:0xf bound_ctrl:1
	v_add_f32_dpp v3, v3, v3 quad_perm:[1,0,3,2] row_mask:0xf bank_mask:0xf bound_ctrl:1
	s_lshl_b32 s22, s20, 12
	s_nop 0
	s_cmp_eq_u32 s20, 1
	v_lshl_add_u32 v1, v97, 2, s21
	v_add_f32_dpp v2, v2, v2 quad_perm:[2,3,0,1] row_mask:0xf bank_mask:0xf bound_ctrl:1
	v_add_f32_dpp v3, v3, v3 quad_perm:[2,3,0,1] row_mask:0xf bank_mask:0xf bound_ctrl:1
	s_cselect_b32 s20, 0x6000, 0
	s_nop 0
	v_lshl_add_u32 v73, v98, 2, s21
	v_add_u32_e32 v74, s20, v143
	ds_read_b128 v[152:155], v1 offset:6912
	ds_read_b128 v[156:159], v1 offset:6928
	ds_read_b128 v[166:169], v1 offset:11008
	ds_read_b128 v[170:173], v1 offset:11024
	ds_read_b128 v[174:177], v1 offset:15104
	ds_read_b128 v[178:181], v1 offset:15120
	ds_read_b128 v[198:201], v1 offset:19200
	ds_read_b128 v[202:205], v1 offset:19216
	ds_read_b64 v[160:161], v73 offset:23296
	ds_read_b128 v[40:43], v74 offset:3072
	ds_read_b128 v[36:39], v74 offset:3088
	v_add_f32_dpp v28, v2, v2 row_half_mirror row_mask:0xf bank_mask:0xf bound_ctrl:1
	v_add_f32_dpp v29, v3, v3 row_half_mirror row_mask:0xf bank_mask:0xf bound_ctrl:1
	s_waitcnt lgkmcnt(6)
	v_pk_mul_f32 v[2:3], v[166:167], v[28:29] op_sel_hi:[0,1]
	s_waitcnt lgkmcnt(2)
	v_pk_fma_f32 v[2:3], v[174:175], v[160:161], v[2:3] op_sel_hi:[0,1,1] neg_lo:[0,0,1] neg_hi:[0,0,1]
	v_pk_fma_f32 v[2:3], v[70:71], v[152:153], v[2:3] op_sel_hi:[1,0,1]
	v_pk_mul_f32 v[30:31], v[166:167], v[28:29] op_sel:[1,0]
	v_pk_mul_f32 v[34:35], v[168:169], v[28:29] op_sel_hi:[0,1]
	v_pk_fma_f32 v[30:31], v[174:175], v[160:161], v[30:31] op_sel:[1,0,0] neg_lo:[0,0,1] neg_hi:[0,0,1]
	v_pk_fma_f32 v[34:35], v[176:177], v[160:161], v[34:35] op_sel_hi:[0,1,1] neg_lo:[0,0,1] neg_hi:[0,0,1]
	v_pk_mul_f32 v[70:71], v[168:169], v[28:29] op_sel:[1,0]
	v_pk_fma_f32 v[68:69], v[68:69], v[152:153], v[30:31] op_sel:[0,1,0]
	v_pk_fma_f32 v[66:67], v[66:67], v[154:155], v[34:35] op_sel_hi:[1,0,1]
	v_pk_fma_f32 v[70:71], v[176:177], v[160:161], v[70:71] op_sel:[1,0,0] neg_lo:[0,0,1] neg_hi:[0,0,1]
	v_pk_fma_f32 v[32:33], v[198:199], v[68:69], 0 op_sel:[1,0,0] op_sel_hi:[1,1,0]
	v_pk_fma_f32 v[64:65], v[64:65], v[154:155], v[70:71] op_sel:[0,1,0]
	v_pk_fma_f32 v[32:33], v[200:201], v[64:65], v[32:33] op_sel:[1,0,0]
	v_pk_mul_f32 v[34:35], v[170:171], v[28:29] op_sel_hi:[0,1]
	v_pk_fma_f32 v[34:35], v[178:179], v[160:161], v[34:35] op_sel_hi:[0,1,1] neg_lo:[0,0,1] neg_hi:[0,0,1]
	v_pk_fma_f32 v[62:63], v[62:63], v[156:157], v[34:35] op_sel_hi:[1,0,1]
	v_pk_mul_f32 v[34:35], v[170:171], v[28:29] op_sel:[1,0]
	v_pk_fma_f32 v[30:31], v[198:199], v[2:3], 0 op_sel_hi:[0,1,0]
	v_pk_fma_f32 v[34:35], v[178:179], v[160:161], v[34:35] op_sel:[1,0,0] neg_lo:[0,0,1] neg_hi:[0,0,1]
	v_pk_fma_f32 v[60:61], v[60:61], v[156:157], v[34:35] op_sel:[0,1,0]
	v_pk_mul_f32 v[34:35], v[172:173], v[28:29] op_sel_hi:[0,1]
	v_pk_fma_f32 v[30:31], v[200:201], v[66:67], v[30:31] op_sel_hi:[0,1,1]
	v_pk_fma_f32 v[34:35], v[180:181], v[160:161], v[34:35] op_sel_hi:[0,1,1] neg_lo:[0,0,1] neg_hi:[0,0,1]
	v_pk_mul_f32 v[28:29], v[172:173], v[28:29] op_sel:[1,0]
	v_pk_fma_f32 v[30:31], v[202:203], v[62:63], v[30:31] op_sel_hi:[0,1,1]
	v_pk_fma_f32 v[46:47], v[46:47], v[158:159], v[34:35] op_sel_hi:[1,0,1]
	v_pk_fma_f32 v[28:29], v[180:181], v[160:161], v[28:29] op_sel:[1,0,0] neg_lo:[0,0,1] neg_hi:[0,0,1]
	v_pk_fma_f32 v[32:33], v[202:203], v[60:61], v[32:33] op_sel:[1,0,0]
	v_pk_fma_f32 v[44:45], v[44:45], v[158:159], v[28:29] op_sel:[0,1,0]
	v_pk_fma_f32 v[28:29], v[204:205], v[46:47], v[30:31] op_sel_hi:[0,1,1]
	v_pk_fma_f32 v[30:31], v[204:205], v[44:45], v[32:33] op_sel:[1,0,0]
	v_pk_add_f32 v[28:29], v[28:29], v[30:31]
	v_add_u32_e32 v72, s22, v99
	s_nop 0
	v_add_f32_dpp v28, v28, v28 quad_perm:[1,0,3,2] row_mask:0xf bank_mask:0xf bound_ctrl:1
	v_add_f32_dpp v29, v29, v29 quad_perm:[1,0,3,2] row_mask:0xf bank_mask:0xf bound_ctrl:1
	s_nop 0
	v_add_f32_dpp v28, v28, v28 quad_perm:[2,3,0,1] row_mask:0xf bank_mask:0xf bound_ctrl:1
	v_add_f32_dpp v29, v29, v29 quad_perm:[2,3,0,1] row_mask:0xf bank_mask:0xf bound_ctrl:1
	s_nop 0
	v_mov_b32_dpp v30, v28 row_half_mirror row_mask:0xf bank_mask:0xf bound_ctrl:1
	v_mov_b32_dpp v31, v29 row_half_mirror row_mask:0xf bank_mask:0xf bound_ctrl:1
	s_and_saveexec_b64 s[20:21], s[14:15]
	v_pk_add_f32 v[28:29], v[28:29], v[30:31]
	ds_write_b64 v72, v[28:29] offset:51968
	s_or_b64 exec, exec, s[20:21]
	s_waitcnt lgkmcnt(1)
	v_pk_mul_f32 v[160:161], v[42:43], v[66:67] op_sel_hi:[0,1]
	v_pk_fma_f32 v[160:161], v[40:41], v[2:3], v[160:161] op_sel_hi:[0,1,1]
	v_pk_mul_f32 v[42:43], v[42:43], v[64:65] op_sel:[1,0]
	v_pk_fma_f32 v[40:41], v[40:41], v[68:69], v[42:43] op_sel:[1,0,0]
	s_waitcnt lgkmcnt(0)
	v_pk_fma_f32 v[42:43], v[36:37], v[62:63], v[160:161] op_sel_hi:[0,1,1]
	v_pk_fma_f32 v[36:37], v[36:37], v[60:61], v[40:41] op_sel:[1,0,0]
	v_pk_fma_f32 v[40:41], v[38:39], v[46:47], v[42:43] op_sel_hi:[0,1,1]
	v_pk_fma_f32 v[36:37], v[38:39], v[44:45], v[36:37] op_sel:[1,0,0]
	v_pk_add_f32 v[36:37], v[40:41], v[36:37]
	ds_read_b128 v[152:155], v1 offset:7168
	ds_read_b128 v[156:159], v1 offset:7184
	ds_read_b128 v[166:169], v1 offset:11264
	ds_read_b128 v[170:173], v1 offset:11280
	ds_read_b128 v[174:177], v1 offset:15360
	ds_read_b128 v[178:181], v1 offset:15376
	ds_read_b128 v[198:201], v1 offset:19456
	ds_read_b128 v[202:205], v1 offset:19472
	ds_read_b64 v[70:71], v73 offset:23552
	ds_read_b128 v[32:35], v74 offset:3328
	ds_read_b128 v[28:31], v74 offset:3344
	v_add_f32_dpp v36, v36, v36 quad_perm:[1,0,3,2] row_mask:0xf bank_mask:0xf bound_ctrl:1
	v_add_f32_dpp v37, v37, v37 quad_perm:[1,0,3,2] row_mask:0xf bank_mask:0xf bound_ctrl:1
	s_nop 0
	v_add_f32_dpp v36, v36, v36 quad_perm:[2,3,0,1] row_mask:0xf bank_mask:0xf bound_ctrl:1
	v_add_f32_dpp v37, v37, v37 quad_perm:[2,3,0,1] row_mask:0xf bank_mask:0xf bound_ctrl:1
	s_nop 0
	v_add_f32_dpp v36, v36, v36 row_half_mirror row_mask:0xf bank_mask:0xf bound_ctrl:1
	v_add_f32_dpp v37, v37, v37 row_half_mirror row_mask:0xf bank_mask:0xf bound_ctrl:1
	s_waitcnt lgkmcnt(8)
	v_pk_mul_f32 v[38:39], v[166:167], v[36:37] op_sel_hi:[0,1]
	s_waitcnt lgkmcnt(2)
	v_pk_fma_f32 v[38:39], v[174:175], v[70:71], v[38:39] op_sel_hi:[0,1,1] neg_lo:[0,0,1] neg_hi:[0,0,1]
	v_pk_fma_f32 v[2:3], v[2:3], v[152:153], v[38:39] op_sel_hi:[1,0,1]
	v_pk_mul_f32 v[38:39], v[166:167], v[36:37] op_sel:[1,0]
	v_pk_mul_f32 v[42:43], v[168:169], v[36:37] op_sel_hi:[0,1]
	v_pk_fma_f32 v[38:39], v[174:175], v[70:71], v[38:39] op_sel:[1,0,0] neg_lo:[0,0,1] neg_hi:[0,0,1]
	v_pk_fma_f32 v[42:43], v[176:177], v[70:71], v[42:43] op_sel_hi:[0,1,1] neg_lo:[0,0,1] neg_hi:[0,0,1]
	v_pk_fma_f32 v[68:69], v[68:69], v[152:153], v[38:39] op_sel:[0,1,0]
	v_pk_fma_f32 v[66:67], v[66:67], v[154:155], v[42:43] op_sel_hi:[1,0,1]
	v_pk_mul_f32 v[152:153], v[168:169], v[36:37] op_sel:[1,0]
	v_pk_fma_f32 v[152:153], v[176:177], v[70:71], v[152:153] op_sel:[1,0,0] neg_lo:[0,0,1] neg_hi:[0,0,1]
	v_pk_fma_f32 v[40:41], v[198:199], v[68:69], 0 op_sel:[1,0,0] op_sel_hi:[1,1,0]
	v_pk_fma_f32 v[64:65], v[64:65], v[154:155], v[152:153] op_sel:[0,1,0]
	v_pk_fma_f32 v[40:41], v[200:201], v[64:65], v[40:41] op_sel:[1,0,0]
	v_pk_mul_f32 v[42:43], v[170:171], v[36:37] op_sel_hi:[0,1]
	v_pk_fma_f32 v[42:43], v[178:179], v[70:71], v[42:43] op_sel_hi:[0,1,1] neg_lo:[0,0,1] neg_hi:[0,0,1]
	v_pk_fma_f32 v[62:63], v[62:63], v[156:157], v[42:43] op_sel_hi:[1,0,1]
	v_pk_mul_f32 v[42:43], v[170:171], v[36:37] op_sel:[1,0]
	v_pk_fma_f32 v[38:39], v[198:199], v[2:3], 0 op_sel_hi:[0,1,0]
	v_pk_fma_f32 v[42:43], v[178:179], v[70:71], v[42:43] op_sel:[1,0,0] neg_lo:[0,0,1] neg_hi:[0,0,1]
	v_pk_fma_f32 v[60:61], v[60:61], v[156:157], v[42:43] op_sel:[0,1,0]
	v_pk_mul_f32 v[42:43], v[172:173], v[36:37] op_sel_hi:[0,1]
	v_pk_fma_f32 v[38:39], v[200:201], v[66:67], v[38:39] op_sel_hi:[0,1,1]
	v_pk_fma_f32 v[42:43], v[180:181], v[70:71], v[42:43] op_sel_hi:[0,1,1] neg_lo:[0,0,1] neg_hi:[0,0,1]
	v_pk_mul_f32 v[36:37], v[172:173], v[36:37] op_sel:[1,0]
	v_pk_fma_f32 v[38:39], v[202:203], v[62:63], v[38:39] op_sel_hi:[0,1,1]
	v_pk_fma_f32 v[46:47], v[46:47], v[158:159], v[42:43] op_sel_hi:[1,0,1]
	v_pk_fma_f32 v[36:37], v[180:181], v[70:71], v[36:37] op_sel:[1,0,0] neg_lo:[0,0,1] neg_hi:[0,0,1]
	v_pk_fma_f32 v[40:41], v[202:203], v[60:61], v[40:41] op_sel:[1,0,0]
	v_pk_fma_f32 v[44:45], v[44:45], v[158:159], v[36:37] op_sel:[0,1,0]
	v_pk_fma_f32 v[36:37], v[204:205], v[46:47], v[38:39] op_sel_hi:[0,1,1]
	v_pk_fma_f32 v[38:39], v[204:205], v[44:45], v[40:41] op_sel:[1,0,0]
	v_pk_add_f32 v[36:37], v[36:37], v[38:39]
	s_nop 1
	v_add_f32_dpp v36, v36, v36 quad_perm:[1,0,3,2] row_mask:0xf bank_mask:0xf bound_ctrl:1
	v_add_f32_dpp v37, v37, v37 quad_perm:[1,0,3,2] row_mask:0xf bank_mask:0xf bound_ctrl:1
	s_nop 0
	v_add_f32_dpp v36, v36, v36 quad_perm:[2,3,0,1] row_mask:0xf bank_mask:0xf bound_ctrl:1
	v_add_f32_dpp v37, v37, v37 quad_perm:[2,3,0,1] row_mask:0xf bank_mask:0xf bound_ctrl:1
	s_nop 0
	v_mov_b32_dpp v38, v36 row_half_mirror row_mask:0xf bank_mask:0xf bound_ctrl:1
	v_mov_b32_dpp v39, v37 row_half_mirror row_mask:0xf bank_mask:0xf bound_ctrl:1
	s_and_saveexec_b64 s[20:21], s[14:15]
	v_pk_add_f32 v[36:37], v[36:37], v[38:39]
	ds_write_b64 v72, v[36:37] offset:52224
	s_or_b64 exec, exec, s[20:21]
	s_waitcnt lgkmcnt(1)
	v_pk_mul_f32 v[160:161], v[34:35], v[66:67] op_sel_hi:[0,1]
	v_pk_fma_f32 v[160:161], v[32:33], v[2:3], v[160:161] op_sel_hi:[0,1,1]
	v_pk_mul_f32 v[34:35], v[34:35], v[64:65] op_sel:[1,0]
	v_pk_fma_f32 v[32:33], v[32:33], v[68:69], v[34:35] op_sel:[1,0,0]
	s_waitcnt lgkmcnt(0)
	v_pk_fma_f32 v[34:35], v[28:29], v[62:63], v[160:161] op_sel_hi:[0,1,1]
	v_pk_fma_f32 v[28:29], v[28:29], v[60:61], v[32:33] op_sel:[1,0,0]
	v_pk_fma_f32 v[32:33], v[30:31], v[46:47], v[34:35] op_sel_hi:[0,1,1]
	v_pk_fma_f32 v[28:29], v[30:31], v[44:45], v[28:29] op_sel:[1,0,0]
	v_pk_add_f32 v[28:29], v[32:33], v[28:29]
	ds_read_b128 v[152:155], v1 offset:7424
	ds_read_b128 v[156:159], v1 offset:7440
	ds_read_b128 v[166:169], v1 offset:11520
	ds_read_b128 v[170:173], v1 offset:11536
	ds_read_b128 v[174:177], v1 offset:15616
	ds_read_b128 v[178:181], v1 offset:15632
	ds_read_b128 v[198:201], v1 offset:19712
	ds_read_b128 v[202:205], v1 offset:19728
	ds_read_b64 v[70:71], v73 offset:23808
	ds_read_b128 v[40:43], v74 offset:3584
	ds_read_b128 v[36:39], v74 offset:3600
	v_add_f32_dpp v28, v28, v28 quad_perm:[1,0,3,2] row_mask:0xf bank_mask:0xf bound_ctrl:1
	v_add_f32_dpp v29, v29, v29 quad_perm:[1,0,3,2] row_mask:0xf bank_mask:0xf bound_ctrl:1
	s_nop 0
	v_add_f32_dpp v28, v28, v28 quad_perm:[2,3,0,1] row_mask:0xf bank_mask:0xf bound_ctrl:1
	v_add_f32_dpp v29, v29, v29 quad_perm:[2,3,0,1] row_mask:0xf bank_mask:0xf bound_ctrl:1
	s_nop 0
	v_add_f32_dpp v28, v28, v28 row_half_mirror row_mask:0xf bank_mask:0xf bound_ctrl:1
	v_add_f32_dpp v29, v29, v29 row_half_mirror row_mask:0xf bank_mask:0xf bound_ctrl:1
	s_waitcnt lgkmcnt(8)
	v_pk_mul_f32 v[30:31], v[166:167], v[28:29] op_sel_hi:[0,1]
	s_waitcnt lgkmcnt(2)
	v_pk_fma_f32 v[30:31], v[174:175], v[70:71], v[30:31] op_sel_hi:[0,1,1] neg_lo:[0,0,1] neg_hi:[0,0,1]
	v_pk_fma_f32 v[2:3], v[2:3], v[152:153], v[30:31] op_sel_hi:[1,0,1]
	v_pk_mul_f32 v[30:31], v[166:167], v[28:29] op_sel:[1,0]
	v_pk_mul_f32 v[34:35], v[168:169], v[28:29] op_sel_hi:[0,1]
	v_pk_fma_f32 v[30:31], v[174:175], v[70:71], v[30:31] op_sel:[1,0,0] neg_lo:[0,0,1] neg_hi:[0,0,1]
	v_pk_fma_f32 v[34:35], v[176:177], v[70:71], v[34:35] op_sel_hi:[0,1,1] neg_lo:[0,0,1] neg_hi:[0,0,1]
	v_pk_fma_f32 v[68:69], v[68:69], v[152:153], v[30:31] op_sel:[0,1,0]
	v_pk_fma_f32 v[66:67], v[66:67], v[154:155], v[34:35] op_sel_hi:[1,0,1]
	v_pk_mul_f32 v[152:153], v[168:169], v[28:29] op_sel:[1,0]
	v_pk_fma_f32 v[152:153], v[176:177], v[70:71], v[152:153] op_sel:[1,0,0] neg_lo:[0,0,1] neg_hi:[0,0,1]
	v_pk_fma_f32 v[32:33], v[198:199], v[68:69], 0 op_sel:[1,0,0] op_sel_hi:[1,1,0]
	v_pk_fma_f32 v[64:65], v[64:65], v[154:155], v[152:153] op_sel:[0,1,0]
	v_pk_fma_f32 v[32:33], v[200:201], v[64:65], v[32:33] op_sel:[1,0,0]
	v_pk_mul_f32 v[34:35], v[170:171], v[28:29] op_sel_hi:[0,1]
	v_pk_fma_f32 v[34:35], v[178:179], v[70:71], v[34:35] op_sel_hi:[0,1,1] neg_lo:[0,0,1] neg_hi:[0,0,1]
	v_pk_fma_f32 v[62:63], v[62:63], v[156:157], v[34:35] op_sel_hi:[1,0,1]
	v_pk_mul_f32 v[34:35], v[170:171], v[28:29] op_sel:[1,0]
	v_pk_fma_f32 v[30:31], v[198:199], v[2:3], 0 op_sel_hi:[0,1,0]
	v_pk_fma_f32 v[34:35], v[178:179], v[70:71], v[34:35] op_sel:[1,0,0] neg_lo:[0,0,1] neg_hi:[0,0,1]
	v_pk_fma_f32 v[60:61], v[60:61], v[156:157], v[34:35] op_sel:[0,1,0]
	v_pk_mul_f32 v[34:35], v[172:173], v[28:29] op_sel_hi:[0,1]
	v_pk_fma_f32 v[30:31], v[200:201], v[66:67], v[30:31] op_sel_hi:[0,1,1]
	v_pk_fma_f32 v[34:35], v[180:181], v[70:71], v[34:35] op_sel_hi:[0,1,1] neg_lo:[0,0,1] neg_hi:[0,0,1]
	v_pk_mul_f32 v[28:29], v[172:173], v[28:29] op_sel:[1,0]
	v_pk_fma_f32 v[30:31], v[202:203], v[62:63], v[30:31] op_sel_hi:[0,1,1]
	v_pk_fma_f32 v[46:47], v[46:47], v[158:159], v[34:35] op_sel_hi:[1,0,1]
	v_pk_fma_f32 v[28:29], v[180:181], v[70:71], v[28:29] op_sel:[1,0,0] neg_lo:[0,0,1] neg_hi:[0,0,1]
	v_pk_fma_f32 v[32:33], v[202:203], v[60:61], v[32:33] op_sel:[1,0,0]
	v_pk_fma_f32 v[44:45], v[44:45], v[158:159], v[28:29] op_sel:[0,1,0]
	v_pk_fma_f32 v[28:29], v[204:205], v[46:47], v[30:31] op_sel_hi:[0,1,1]
	v_pk_fma_f32 v[30:31], v[204:205], v[44:45], v[32:33] op_sel:[1,0,0]
	v_pk_add_f32 v[28:29], v[28:29], v[30:31]
	s_nop 1
	v_add_f32_dpp v28, v28, v28 quad_perm:[1,0,3,2] row_mask:0xf bank_mask:0xf bound_ctrl:1
	v_add_f32_dpp v29, v29, v29 quad_perm:[1,0,3,2] row_mask:0xf bank_mask:0xf bound_ctrl:1
	s_nop 0
	v_add_f32_dpp v28, v28, v28 quad_perm:[2,3,0,1] row_mask:0xf bank_mask:0xf bound_ctrl:1
	v_add_f32_dpp v29, v29, v29 quad_perm:[2,3,0,1] row_mask:0xf bank_mask:0xf bound_ctrl:1
	s_nop 0
	v_mov_b32_dpp v30, v28 row_half_mirror row_mask:0xf bank_mask:0xf bound_ctrl:1
	v_mov_b32_dpp v31, v29 row_half_mirror row_mask:0xf bank_mask:0xf bound_ctrl:1
	s_and_saveexec_b64 s[20:21], s[14:15]
	v_pk_add_f32 v[28:29], v[28:29], v[30:31]
	ds_write_b64 v72, v[28:29] offset:52480
	s_or_b64 exec, exec, s[20:21]
	ds_read_b128 v[152:155], v1 offset:7680
	ds_read_b128 v[156:159], v1 offset:7696
	ds_read_b128 v[166:169], v1 offset:11776
	ds_read_b128 v[170:173], v1 offset:11792
	ds_read_b128 v[174:177], v1 offset:15872
	ds_read_b128 v[178:181], v1 offset:15888
	ds_read_b128 v[198:201], v1 offset:19968
	ds_read_b128 v[202:205], v1 offset:19984
	ds_read_b64 v[70:71], v73 offset:24064
	ds_read_b128 v[32:35], v74 offset:3840
	ds_read_b128 v[28:31], v74 offset:3856
	s_waitcnt lgkmcnt(12)
	v_pk_mul_f32 v[74:75], v[42:43], v[66:67] op_sel_hi:[0,1]
	v_pk_fma_f32 v[74:75], v[40:41], v[2:3], v[74:75] op_sel_hi:[0,1,1]
	v_pk_mul_f32 v[42:43], v[42:43], v[64:65] op_sel:[1,0]
	v_pk_fma_f32 v[40:41], v[40:41], v[68:69], v[42:43] op_sel:[1,0,0]
	s_waitcnt lgkmcnt(11)
	v_pk_fma_f32 v[42:43], v[36:37], v[62:63], v[74:75] op_sel_hi:[0,1,1]
	v_pk_fma_f32 v[36:37], v[36:37], v[60:61], v[40:41] op_sel:[1,0,0]
	v_pk_fma_f32 v[40:41], v[38:39], v[46:47], v[42:43] op_sel_hi:[0,1,1]
	v_pk_fma_f32 v[36:37], v[38:39], v[44:45], v[36:37] op_sel:[1,0,0]
	v_pk_add_f32 v[36:37], v[40:41], v[36:37]
	s_waitcnt lgkmcnt(10)
	s_nop 0
	v_add_f32_dpp v36, v36, v36 quad_perm:[1,0,3,2] row_mask:0xf bank_mask:0xf bound_ctrl:1
	v_add_f32_dpp v37, v37, v37 quad_perm:[1,0,3,2] row_mask:0xf bank_mask:0xf bound_ctrl:1
	s_nop 0
	v_add_f32_dpp v36, v36, v36 quad_perm:[2,3,0,1] row_mask:0xf bank_mask:0xf bound_ctrl:1
	v_add_f32_dpp v37, v37, v37 quad_perm:[2,3,0,1] row_mask:0xf bank_mask:0xf bound_ctrl:1
	s_nop 0
	v_add_f32_dpp v74, v36, v36 row_half_mirror row_mask:0xf bank_mask:0xf bound_ctrl:1
	v_add_f32_dpp v75, v37, v37 row_half_mirror row_mask:0xf bank_mask:0xf bound_ctrl:1
	s_waitcnt lgkmcnt(8)
	v_pk_mul_f32 v[36:37], v[166:167], v[74:75] op_sel_hi:[0,1]
	s_waitcnt lgkmcnt(2)
	v_pk_fma_f32 v[36:37], v[174:175], v[70:71], v[36:37] op_sel_hi:[0,1,1] neg_lo:[0,0,1] neg_hi:[0,0,1]
	v_pk_mul_f32 v[38:39], v[168:169], v[74:75] op_sel_hi:[0,1]
	v_pk_fma_f32 v[2:3], v[2:3], v[152:153], v[36:37] op_sel_hi:[1,0,1]
	v_pk_mul_f32 v[36:37], v[166:167], v[74:75] op_sel:[1,0]
	v_pk_fma_f32 v[38:39], v[176:177], v[70:71], v[38:39] op_sel_hi:[0,1,1] neg_lo:[0,0,1] neg_hi:[0,0,1]
	v_pk_fma_f32 v[36:37], v[174:175], v[70:71], v[36:37] op_sel:[1,0,0] neg_lo:[0,0,1] neg_hi:[0,0,1]
	v_pk_fma_f32 v[38:39], v[66:67], v[154:155], v[38:39] op_sel_hi:[1,0,1]
	v_pk_fma_f32 v[36:37], v[68:69], v[152:153], v[36:37] op_sel:[0,1,0]
	v_pk_mul_f32 v[66:67], v[168:169], v[74:75] op_sel:[1,0]
	v_pk_fma_f32 v[42:43], v[198:199], v[2:3], 0 op_sel_hi:[0,1,0]
	v_pk_fma_f32 v[66:67], v[176:177], v[70:71], v[66:67] op_sel:[1,0,0] neg_lo:[0,0,1] neg_hi:[0,0,1]
	v_pk_fma_f32 v[68:69], v[198:199], v[36:37], 0 op_sel:[1,0,0] op_sel_hi:[1,1,0]
	v_pk_fma_f32 v[40:41], v[64:65], v[154:155], v[66:67] op_sel:[0,1,0]
	v_pk_fma_f32 v[64:65], v[200:201], v[38:39], v[42:43] op_sel_hi:[0,1,1]
	v_pk_fma_f32 v[66:67], v[200:201], v[40:41], v[68:69] op_sel:[1,0,0]
	v_pk_mul_f32 v[42:43], v[170:171], v[74:75] op_sel_hi:[0,1]
	v_pk_fma_f32 v[42:43], v[178:179], v[70:71], v[42:43] op_sel_hi:[0,1,1] neg_lo:[0,0,1] neg_hi:[0,0,1]
	v_pk_fma_f32 v[42:43], v[62:63], v[156:157], v[42:43] op_sel_hi:[1,0,1]
	v_pk_mul_f32 v[62:63], v[170:171], v[74:75] op_sel:[1,0]
	v_pk_fma_f32 v[62:63], v[178:179], v[70:71], v[62:63] op_sel:[1,0,0] neg_lo:[0,0,1] neg_hi:[0,0,1]
	v_pk_fma_f32 v[60:61], v[60:61], v[156:157], v[62:63] op_sel:[0,1,0]
	v_pk_fma_f32 v[62:63], v[202:203], v[42:43], v[64:65] op_sel_hi:[0,1,1]
	v_pk_fma_f32 v[64:65], v[202:203], v[60:61], v[66:67] op_sel:[1,0,0]
	v_pk_mul_f32 v[66:67], v[172:173], v[74:75] op_sel_hi:[0,1]
	v_pk_fma_f32 v[66:67], v[180:181], v[70:71], v[66:67] op_sel_hi:[0,1,1] neg_lo:[0,0,1] neg_hi:[0,0,1]
	v_pk_mul_f32 v[68:69], v[172:173], v[74:75] op_sel:[1,0]
	v_pk_fma_f32 v[46:47], v[46:47], v[158:159], v[66:67] op_sel_hi:[1,0,1]
	v_pk_fma_f32 v[68:69], v[180:181], v[70:71], v[68:69] op_sel:[1,0,0] neg_lo:[0,0,1] neg_hi:[0,0,1]
	v_pk_fma_f32 v[44:45], v[44:45], v[158:159], v[68:69] op_sel:[0,1,0]
	v_pk_fma_f32 v[62:63], v[204:205], v[46:47], v[62:63] op_sel_hi:[0,1,1]
	v_pk_fma_f32 v[64:65], v[204:205], v[44:45], v[64:65] op_sel:[1,0,0]
	v_pk_add_f32 v[62:63], v[62:63], v[64:65]
	s_nop 1
	v_add_f32_dpp v62, v62, v62 quad_perm:[1,0,3,2] row_mask:0xf bank_mask:0xf bound_ctrl:1
	v_add_f32_dpp v63, v63, v63 quad_perm:[1,0,3,2] row_mask:0xf bank_mask:0xf bound_ctrl:1
	s_nop 0
	v_add_f32_dpp v62, v62, v62 quad_perm:[2,3,0,1] row_mask:0xf bank_mask:0xf bound_ctrl:1
	v_add_f32_dpp v63, v63, v63 quad_perm:[2,3,0,1] row_mask:0xf bank_mask:0xf bound_ctrl:1
	s_nop 0
	v_mov_b32_dpp v64, v62 row_half_mirror row_mask:0xf bank_mask:0xf bound_ctrl:1
	v_mov_b32_dpp v65, v63 row_half_mirror row_mask:0xf bank_mask:0xf bound_ctrl:1
	s_and_saveexec_b64 s[20:21], s[14:15]
	v_pk_add_f32 v[62:63], v[62:63], v[64:65]
	ds_write_b64 v72, v[62:63] offset:52736
	s_or_b64 exec, exec, s[20:21]
	s_waitcnt lgkmcnt(1)
	v_pk_mul_f32 v[66:67], v[34:35], v[38:39] op_sel_hi:[0,1]
	v_pk_mul_f32 v[68:69], v[34:35], v[40:41] op_sel:[1,0]
	v_pk_fma_f32 v[66:67], v[32:33], v[2:3], v[66:67] op_sel_hi:[0,1,1]
	v_pk_fma_f32 v[68:69], v[32:33], v[36:37], v[68:69] op_sel:[1,0,0]
	s_waitcnt lgkmcnt(0)
	v_pk_fma_f32 v[66:67], v[28:29], v[42:43], v[66:67] op_sel_hi:[0,1,1]
	v_pk_fma_f32 v[68:69], v[28:29], v[60:61], v[68:69] op_sel:[1,0,0]
	v_pk_fma_f32 v[66:67], v[30:31], v[46:47], v[66:67] op_sel_hi:[0,1,1]
	v_pk_fma_f32 v[68:69], v[30:31], v[44:45], v[68:69] op_sel:[1,0,0]
	v_pk_add_f32 v[66:67], v[66:67], v[68:69]
	ds_read_b64 v[74:75], v73 offset:24320
	ds_read_b128 v[152:155], v1 offset:20240
	ds_read_b128 v[156:159], v1 offset:20224
	ds_read_b128 v[166:169], v1 offset:16144
	ds_read_b128 v[62:65], v1 offset:16128
	ds_read_b128 v[170:173], v1 offset:12048
	ds_read_b128 v[174:177], v1 offset:12032
	ds_read_b128 v[178:181], v1 offset:7936
	ds_read_b128 v[198:201], v1 offset:7952
	v_add_f32_dpp v66, v66, v66 quad_perm:[1,0,3,2] row_mask:0xf bank_mask:0xf bound_ctrl:1
	v_add_f32_dpp v67, v67, v67 quad_perm:[1,0,3,2] row_mask:0xf bank_mask:0xf bound_ctrl:1
	s_nop 0
	v_add_f32_dpp v66, v66, v66 quad_perm:[2,3,0,1] row_mask:0xf bank_mask:0xf bound_ctrl:1
	v_add_f32_dpp v67, v67, v67 quad_perm:[2,3,0,1] row_mask:0xf bank_mask:0xf bound_ctrl:1
	s_nop 0
	v_add_f32_dpp v160, v66, v66 row_half_mirror row_mask:0xf bank_mask:0xf bound_ctrl:1
	v_add_f32_dpp v161, v67, v67 row_half_mirror row_mask:0xf bank_mask:0xf bound_ctrl:1
	s_waitcnt lgkmcnt(2)
	v_pk_mul_f32 v[66:67], v[174:175], v[160:161] op_sel_hi:[0,1]
	v_pk_fma_f32 v[66:67], v[74:75], v[62:63], v[66:67] op_sel_hi:[1,0,1] neg_lo:[0,0,1] neg_hi:[0,0,1]
	s_waitcnt lgkmcnt(1)
	v_pk_fma_f32 v[70:71], v[2:3], v[178:179], v[66:67] op_sel_hi:[1,0,1]
	v_pk_mul_f32 v[2:3], v[174:175], v[160:161] op_sel:[1,0]
	s_nop 0
	v_pk_fma_f32 v[2:3], v[74:75], v[62:63], v[2:3] op_sel:[0,1,0] neg_lo:[0,0,1] neg_hi:[0,0,1]
	v_pk_mul_f32 v[62:63], v[176:177], v[160:161] op_sel_hi:[0,1]
	v_pk_fma_f32 v[62:63], v[74:75], v[64:65], v[62:63] op_sel_hi:[1,0,1] neg_lo:[0,0,1] neg_hi:[0,0,1]
	v_pk_fma_f32 v[66:67], v[38:39], v[180:181], v[62:63] op_sel_hi:[1,0,1]
	v_pk_mul_f32 v[62:63], v[176:177], v[160:161] op_sel:[1,0]
	v_pk_fma_f32 v[68:69], v[36:37], v[178:179], v[2:3] op_sel:[0,1,0]
	v_pk_fma_f32 v[62:63], v[74:75], v[64:65], v[62:63] op_sel:[0,1,0] neg_lo:[0,0,1] neg_hi:[0,0,1]
	v_pk_fma_f32 v[36:37], v[156:157], v[68:69], 0 op_sel:[1,0,0] op_sel_hi:[1,1,0]
	v_pk_fma_f32 v[64:65], v[40:41], v[180:181], v[62:63] op_sel:[0,1,0]
	v_pk_fma_f32 v[36:37], v[158:159], v[64:65], v[36:37] op_sel:[1,0,0]
	v_pk_mul_f32 v[38:39], v[170:171], v[160:161] op_sel_hi:[0,1]
	v_pk_fma_f32 v[38:39], v[74:75], v[166:167], v[38:39] op_sel_hi:[1,0,1] neg_lo:[0,0,1] neg_hi:[0,0,1]
	s_waitcnt lgkmcnt(0)
	v_pk_fma_f32 v[62:63], v[42:43], v[198:199], v[38:39] op_sel_hi:[1,0,1]
	v_pk_mul_f32 v[38:39], v[170:171], v[160:161] op_sel:[1,0]
	v_pk_fma_f32 v[2:3], v[156:157], v[70:71], 0 op_sel_hi:[0,1,0]
	v_pk_fma_f32 v[38:39], v[74:75], v[166:167], v[38:39] op_sel:[0,1,0] neg_lo:[0,0,1] neg_hi:[0,0,1]
	v_mov_b32_e32 v42, v169
	v_pk_fma_f32 v[60:61], v[60:61], v[198:199], v[38:39] op_sel:[0,1,0]
	v_pk_mul_f32 v[38:39], v[172:173], v[160:161] op_sel_hi:[0,1]
	v_pk_fma_f32 v[38:39], v[74:75], v[168:169], v[38:39] op_sel_hi:[1,0,1] neg_lo:[0,0,1] neg_hi:[0,0,1]
	v_pk_mul_f32 v[40:41], v[172:173], v[160:161] op_sel:[1,0]
	v_pk_fma_f32 v[2:3], v[158:159], v[66:67], v[2:3] op_sel_hi:[0,1,1]
	v_pk_fma_f32 v[46:47], v[46:47], v[200:201], v[38:39] op_sel_hi:[1,0,1]
	v_pk_fma_f32 v[40:41], v[74:75], v[42:43], v[40:41] op_sel_hi:[1,0,1] neg_lo:[0,0,1] neg_hi:[0,0,1]
	v_pk_fma_f32 v[2:3], v[152:153], v[62:63], v[2:3] op_sel_hi:[0,1,1]
	v_pk_fma_f32 v[36:37], v[152:153], v[60:61], v[36:37] op_sel:[1,0,0]
	v_pk_fma_f32 v[44:45], v[44:45], v[200:201], v[40:41] op_sel:[0,1,0]
	v_mov_b32_e32 v38, v155
	v_pk_fma_f32 v[2:3], v[154:155], v[46:47], v[2:3] op_sel_hi:[0,1,1]
	v_pk_fma_f32 v[36:37], v[38:39], v[44:45], v[36:37] op_sel_hi:[0,1,1]
	v_pk_add_f32 v[2:3], v[2:3], v[36:37]
	s_nop 1
	v_add_f32_dpp v2, v2, v2 quad_perm:[1,0,3,2] row_mask:0xf bank_mask:0xf bound_ctrl:1
	v_add_f32_dpp v3, v3, v3 quad_perm:[1,0,3,2] row_mask:0xf bank_mask:0xf bound_ctrl:1
	s_nop 0
	v_add_f32_dpp v2, v2, v2 quad_perm:[2,3,0,1] row_mask:0xf bank_mask:0xf bound_ctrl:1
	v_add_f32_dpp v3, v3, v3 quad_perm:[2,3,0,1] row_mask:0xf bank_mask:0xf bound_ctrl:1
	s_nop 0
	v_mov_b32_dpp v36, v2 row_half_mirror row_mask:0xf bank_mask:0xf bound_ctrl:1
	v_mov_b32_dpp v37, v3 row_half_mirror row_mask:0xf bank_mask:0xf bound_ctrl:1
	s_and_saveexec_b64 s[20:21], s[14:15]
	s_cbranch_execz .LBB0_575
	v_pk_add_f32 v[2:3], v[2:3], v[36:37]
	ds_write_b64 v72, v[2:3] offset:52992
	s_branch .LBB0_575
